# MLA: first K fragments read before the next tile's DMA issue, first V fragments read right after Q.K (LDS latency behind scalar work / softmax)
# baseline (speedup 1.0000x reference)
; #define WLK(n) do { asm volatile("s_waitcnt lgkmcnt(" #n ")" ::: "memory"); SBAR(); } while (0)
; #define RDN(S, dd, off) do { const int a_ = rb + (((dd) * 32 + h16) ^ sw); KRD(S##0, a_, off); KRD(S##1, a_, 8192 + (off)); } while (0)
; #define RDR(S, ks) do { const int a_ = rr + (((((ks) * 2 + hi)) ^ (r32 & 7)) << 4); KRD(S##0, a_, 0); KRD(S##1, a_, 4096); } while (0)
; #define MM1(S, d) do { p0 = __builtin_amdgcn_mfma_f32_32x32x16_bf16(S##0, qr[d], p0, 0, 0, 0); p1 = __builtin_amdgcn_mfma_f32_32x32x16_bf16(S##1, qr[d], p1, 0, 0, 0); } while (0)
; __device__ __forceinline__ void qk_mla(f32x16& p0, f32x16& p1, int kaddr, int r32, int hi, const bf16x8* qr) {
;     const int rb = kaddr + r32 * 256, sw = (r32 & 7) << 4, h16 = hi * 16;
;     const int rr = kaddr + 16384 + r32 * 128;
;     ...
;     bf16x8 A0, A1, B0, B1;
;     RDN(A, 0, 0); RDN(B, 1, 0);
;     WLK(2); MM1(A, 0); RDN(A, 2, 0);
;     WLK(2); MM1(B, 1); RDN(B, 3, 0);
;     WLK(2); MM1(A, 2); RDN(A, 0, 128);
;     WLK(2); MM1(B, 3); RDN(B, 1, 128);
;     WLK(2); MM1(A, 4); RDN(A, 2, 128);
;     WLK(2); MM1(B, 5); RDN(B, 3, 128);
;     WLK(2); MM1(A, 6); RDR(A, 0);
;     WLK(2); MM1(B, 7); RDR(B, 1);
;     WLK(2); MM1(A, 8); RDR(A, 2);
;     WLK(2); MM1(B, 9); RDR(B, 3);
;     WLK(2); MM1(A, 10);
;     WLK(0); MM1(B, 11);
; template <bool MLA> __device__ __forceinline__ void attn_unit(const AttnP& P, int b, int hh, int qb, LAS char* lds) {
;     ...
;     for (int t = 0; t < NT; ++t) {
;         const int buf = t & 1;
;         if (t + 1 < NT) LOADT(t + 1, buf ^ 1);
;         const int kb = kbase0 + 64 * t;
;         const bool act = (kb <= qlo + 31) && (MLA || kb + 63 >= qlo - (W - 1));
;         if (act) {
;             f32x16 p0 = f32x16{}, p1 = f32x16{};
;             if constexpr (MLA) {
; #pragma unroll
;                 for (int r = 0; r < 16; ++r) { p0[r] = -m_reg; p1[r] = -m_reg; } }
;             if constexpr (MLA) { qk_mla(p0, p1, (int)(uintptr_t)K_lds + buf * KBYTES, r32, hi, qr); }
;             else { qk64(p0, p1, K_lds + buf * KBYTES, r32, hi, qr); }
.Lm16_tile:
	s_and_b32 s58, s41, 1
	s_mul_i32 s70, s58, 0x6000
	s_add_u32 s70, s70, 0x8000
	s_lshl_b32 s71, s58, 14
	s_add_u32 s36, s43, 31
	s_cmp_gt_u32 s42, s36
	s_cbranch_scc1 .Lm16_inactive
	v_add_u32_e32 v228, s70, v224
	v_add_u32_e32 v229, s70, v225
	v_add_u32_e32 v230, s71, v226
	v_add_u32_e32 v231, s71, v227
	ds_read_b128 v[180:183], v228 offset:0
	ds_read_b128 v[184:187], v228 offset:2048
	ds_read_b128 v[188:191], v228 offset:4096
	s_add_u32 s36, s41, 1
	s_cmp_lt_u32 s36, s40
	s_cbranch_scc0 .Lm16_noload
	s_xor_b32 s37, s58, 1
	s_mul_i32 s59, s37, 0x6000
	s_add_u32 s59, s59, 0x8000
	s_lshl_b32 s37, s37, 14
	s_add_i32 s36, s5, s59
	s_mov_b32 m0, s36
	s_nop 0
	global_load_lds_dwordx4 v232, s[46:47]
	s_add_i32 m0, s36, 0x2000
	s_nop 0
	global_load_lds_dwordx4 v233, s[46:47]
	s_add_i32 m0, s36, 0x4000
	s_nop 0
	global_load_lds_dwordx4 v234, s[50:51]
	s_add_i32 s36, s5, s37
	s_mov_b32 m0, s36
	s_nop 0
	global_load_lds_dwordx4 v235, s[48:49]
	s_add_i32 m0, s36, 0x2000
	s_nop 0
	global_load_lds_dwordx4 v236, s[48:49]
	s_add_u32 s46, s46, 0x40000
	s_addc_u32 s47, s47, 0
	s_add_u32 s48, s48, 0x40000
	s_addc_u32 s49, s49, 0
	s_add_u32 s50, s50, 0x2000
	s_addc_u32 s51, s51, 0
.Lm16_noload:
	ds_read_b128 v[192:195], v228 offset:6144
	s_waitcnt lgkmcnt(3)
	v_mfma_f32_16x16x32_bf16 v[114:117], v[180:183], v[66:69], v[208:211]
	v_mfma_f32_16x16x32_bf16 v[118:121], v[180:183], v[90:93], v[212:215]
	ds_read_b128 v[180:183], v229 offset:0
	s_waitcnt lgkmcnt(3)
	v_mfma_f32_16x16x32_bf16 v[122:125], v[184:187], v[66:69], v[208:211]
	v_mfma_f32_16x16x32_bf16 v[126:129], v[184:187], v[90:93], v[212:215]
	ds_read_b128 v[184:187], v229 offset:2048
	s_waitcnt lgkmcnt(3)
	v_mfma_f32_16x16x32_bf16 v[130:133], v[188:191], v[66:69], v[208:211]
	v_mfma_f32_16x16x32_bf16 v[134:137], v[188:191], v[90:93], v[212:215]
	ds_read_b128 v[188:191], v229 offset:4096
	s_waitcnt lgkmcnt(3)
	v_mfma_f32_16x16x32_bf16 v[138:141], v[192:195], v[66:69], v[208:211]
	v_mfma_f32_16x16x32_bf16 v[142:145], v[192:195], v[90:93], v[212:215]
	ds_read_b128 v[192:195], v229 offset:6144
	s_waitcnt lgkmcnt(3)
	v_mfma_f32_16x16x32_bf16 v[114:117], v[180:183], v[70:73], v[114:117]
	v_mfma_f32_16x16x32_bf16 v[118:121], v[180:183], v[94:97], v[118:121]
	ds_read_b128 v[180:183], v228 offset:8192
	s_waitcnt lgkmcnt(3)
	v_mfma_f32_16x16x32_bf16 v[122:125], v[184:187], v[70:73], v[122:125]
	v_mfma_f32_16x16x32_bf16 v[126:129], v[184:187], v[94:97], v[126:129]
	ds_read_b128 v[184:187], v228 offset:10240
	s_waitcnt lgkmcnt(3)
	v_mfma_f32_16x16x32_bf16 v[130:133], v[188:191], v[70:73], v[130:133]
	v_mfma_f32_16x16x32_bf16 v[134:137], v[188:191], v[94:97], v[134:137]
	ds_read_b128 v[188:191], v228 offset:12288
	s_waitcnt lgkmcnt(3)
	v_mfma_f32_16x16x32_bf16 v[138:141], v[192:195], v[70:73], v[138:141]
	v_mfma_f32_16x16x32_bf16 v[142:145], v[192:195], v[94:97], v[142:145]
	ds_read_b128 v[192:195], v228 offset:14336
	s_waitcnt lgkmcnt(3)
	v_mfma_f32_16x16x32_bf16 v[114:117], v[180:183], v[74:77], v[114:117]
	v_mfma_f32_16x16x32_bf16 v[118:121], v[180:183], v[98:101], v[118:121]
	ds_read_b128 v[180:183], v229 offset:8192
	s_waitcnt lgkmcnt(3)
	v_mfma_f32_16x16x32_bf16 v[122:125], v[184:187], v[74:77], v[122:125]
	v_mfma_f32_16x16x32_bf16 v[126:129], v[184:187], v[98:101], v[126:129]
	ds_read_b128 v[184:187], v229 offset:10240
	s_waitcnt lgkmcnt(3)
	v_mfma_f32_16x16x32_bf16 v[130:133], v[188:191], v[74:77], v[130:133]
	v_mfma_f32_16x16x32_bf16 v[134:137], v[188:191], v[98:101], v[134:137]
	ds_read_b128 v[188:191], v229 offset:12288
	s_waitcnt lgkmcnt(3)
	v_mfma_f32_16x16x32_bf16 v[138:141], v[192:195], v[74:77], v[138:141]
	v_mfma_f32_16x16x32_bf16 v[142:145], v[192:195], v[98:101], v[142:145]
	ds_read_b128 v[192:195], v229 offset:14336
	s_waitcnt lgkmcnt(3)
	v_mfma_f32_16x16x32_bf16 v[114:117], v[180:183], v[78:81], v[114:117]
	v_mfma_f32_16x16x32_bf16 v[118:121], v[180:183], v[102:105], v[118:121]
	ds_read_b128 v[180:183], v228 offset:16384
	s_waitcnt lgkmcnt(3)
	v_mfma_f32_16x16x32_bf16 v[122:125], v[184:187], v[78:81], v[122:125]
	v_mfma_f32_16x16x32_bf16 v[126:129], v[184:187], v[102:105], v[126:129]
	ds_read_b128 v[184:187], v228 offset:18432
	s_waitcnt lgkmcnt(3)
	v_mfma_f32_16x16x32_bf16 v[130:133], v[188:191], v[78:81], v[130:133]
	v_mfma_f32_16x16x32_bf16 v[134:137], v[188:191], v[102:105], v[134:137]
	ds_read_b128 v[188:191], v228 offset:20480
	s_waitcnt lgkmcnt(3)
	v_mfma_f32_16x16x32_bf16 v[138:141], v[192:195], v[78:81], v[138:141]
	v_mfma_f32_16x16x32_bf16 v[142:145], v[192:195], v[102:105], v[142:145]
	ds_read_b128 v[192:195], v228 offset:22528
	s_waitcnt lgkmcnt(3)
	v_mfma_f32_16x16x32_bf16 v[114:117], v[180:183], v[82:85], v[114:117]
	v_mfma_f32_16x16x32_bf16 v[118:121], v[180:183], v[106:109], v[118:121]
	ds_read_b128 v[180:183], v229 offset:16384
	s_waitcnt lgkmcnt(3)
	v_mfma_f32_16x16x32_bf16 v[122:125], v[184:187], v[82:85], v[122:125]
	v_mfma_f32_16x16x32_bf16 v[126:129], v[184:187], v[106:109], v[126:129]
	ds_read_b128 v[184:187], v229 offset:18432
	s_waitcnt lgkmcnt(3)
	v_mfma_f32_16x16x32_bf16 v[130:133], v[188:191], v[82:85], v[130:133]
	v_mfma_f32_16x16x32_bf16 v[134:137], v[188:191], v[106:109], v[134:137]
	ds_read_b128 v[188:191], v229 offset:20480
	s_waitcnt lgkmcnt(3)
	v_mfma_f32_16x16x32_bf16 v[138:141], v[192:195], v[82:85], v[138:141]
	v_mfma_f32_16x16x32_bf16 v[142:145], v[192:195], v[106:109], v[142:145]
	ds_read_b128 v[192:195], v229 offset:22528
	s_waitcnt lgkmcnt(3)
	v_mfma_f32_16x16x32_bf16 v[114:117], v[180:183], v[86:89], v[114:117]
	v_mfma_f32_16x16x32_bf16 v[118:121], v[180:183], v[110:113], v[118:121]
	s_waitcnt lgkmcnt(2)
	v_mfma_f32_16x16x32_bf16 v[122:125], v[184:187], v[86:89], v[122:125]
	v_mfma_f32_16x16x32_bf16 v[126:129], v[184:187], v[110:113], v[126:129]
	s_waitcnt lgkmcnt(1)
	v_mfma_f32_16x16x32_bf16 v[130:133], v[188:191], v[86:89], v[130:133]
	v_mfma_f32_16x16x32_bf16 v[134:137], v[188:191], v[110:113], v[134:137]
	s_waitcnt lgkmcnt(0)
	v_mfma_f32_16x16x32_bf16 v[138:141], v[192:195], v[86:89], v[138:141]
	v_mfma_f32_16x16x32_bf16 v[142:145], v[192:195], v[110:113], v[142:145]
	ds_read_b64_tr_b16 v[180:181], v230 offset:0
	ds_read_b64_tr_b16 v[182:183], v230 offset:4096
	ds_read_b64_tr_b16 v[184:185], v230 offset:8192
	ds_read_b64_tr_b16 v[186:187], v230 offset:12288
	ds_read_b64_tr_b16 v[188:189], v231 offset:0
	ds_read_b64_tr_b16 v[190:191], v231 offset:4096
	s_nop 7
	s_add_u32 s36, s42, 63
	s_cmp_gt_u32 s36, s43
	s_cbranch_scc0 .Lm16_nomask
; __device__ __forceinline__ void mask_tile(f32x16& p0, f32x16& p1, int dq, unsigned W) {
;     const float NEG = -__builtin_inff();
; #pragma unroll
;     for (int r = 0; r < 16; ++r) { const int c = (r & 3) + 8 * (r >> 2);
;         if ((unsigned)(dq - c) >= W) p0[r] = NEG;
;         if ((unsigned)(dq - c - 32) >= W) p1[r] = NEG; }
; }
; __device__ __forceinline__ void partialSM_pre(f32x16& p0, f32x16& p1, float& m_reg, float& alpha) {
;     ...
;     if (__builtin_expect(__all(pmax <= THR2), 1)) { alpha = 1.f; }
;     else { const float d = fmaxf(pmax, 0.f); m_reg += d; alpha = __builtin_amdgcn_exp2f(-d);
; #pragma unroll
;         for (int r = 0; r < 16; ++r) { p0[r] -= d; p1[r] -= d; } }
; #pragma unroll
;     for (int r = 0; r < 16; ++r) p0[r] = __builtin_amdgcn_exp2f(p0[r]);
; }
; __device__ __forceinline__ void finishSM(f32x16& p0, f32x16& p1, float alpha, float& l_reg, bf16x8& pa0, bf16x8& pa1, bf16x8& pa2, bf16x8& pa3) {
; #pragma unroll
;     for (int r = 0; r < 16; ++r) p1[r] = __builtin_amdgcn_exp2f(p1[r]);
;     float ps = 0;
; #pragma unroll
;     for (int r = 0; r < 16; ++r) ps += p0[r];
; #pragma unroll
;     for (int r = 0; r < 16; ++r) ps += p1[r];
;     { auto rr = __builtin_amdgcn_permlane32_swap(__float_as_uint(ps), __float_as_uint(ps), false, false);
;       ps = __uint_as_float(rr[0]) + __uint_as_float(rr[1]); }
;     l_reg = l_reg * alpha + ps;
;     ...
;     PK4(p0, 0, pa0); PK4(p0, 8, pa1); PK4(p1, 0, pa2); PK4(p1, 8, pa3);
	s_sub_u32 s36, s43, s42
	v_add_u32_e32 v244, s36, v243
	v_cmp_gt_i32_e32 vcc, 0, v244
	s_nop 1
	v_cndmask_b32_e32 v114, v114, v245, vcc
	v_cmp_gt_i32_e32 vcc, 1, v244
	s_nop 1
	v_cndmask_b32_e32 v115, v115, v245, vcc
	v_cmp_gt_i32_e32 vcc, 2, v244
	s_nop 1
	v_cndmask_b32_e32 v116, v116, v245, vcc
	v_cmp_gt_i32_e32 vcc, 3, v244
	s_nop 1
	v_cndmask_b32_e32 v117, v117, v245, vcc
	v_cmp_gt_i32_e32 vcc, -16, v244
	s_nop 1
	v_cndmask_b32_e32 v118, v118, v245, vcc
	v_cmp_gt_i32_e32 vcc, -15, v244
	s_nop 1
	v_cndmask_b32_e32 v119, v119, v245, vcc
	v_cmp_gt_i32_e32 vcc, -14, v244
	s_nop 1
	v_cndmask_b32_e32 v120, v120, v245, vcc
	v_cmp_gt_i32_e32 vcc, -13, v244
	s_nop 1
	v_cndmask_b32_e32 v121, v121, v245, vcc
	v_cmp_gt_i32_e32 vcc, 16, v244
	s_nop 1
	v_cndmask_b32_e32 v122, v122, v245, vcc
	v_cmp_gt_i32_e32 vcc, 17, v244
	s_nop 1
	v_cndmask_b32_e32 v123, v123, v245, vcc
	v_cmp_gt_i32_e32 vcc, 18, v244
	s_nop 1
	v_cndmask_b32_e32 v124, v124, v245, vcc
	v_cmp_gt_i32_e32 vcc, 19, v244
	s_nop 1
	v_cndmask_b32_e32 v125, v125, v245, vcc
	v_cmp_gt_i32_e32 vcc, 0, v244
	s_nop 1
	v_cndmask_b32_e32 v126, v126, v245, vcc
	v_cmp_gt_i32_e32 vcc, 1, v244
	s_nop 1
	v_cndmask_b32_e32 v127, v127, v245, vcc
	v_cmp_gt_i32_e32 vcc, 2, v244
	s_nop 1
	v_cndmask_b32_e32 v128, v128, v245, vcc
	v_cmp_gt_i32_e32 vcc, 3, v244
	s_nop 1
	v_cndmask_b32_e32 v129, v129, v245, vcc
	v_cmp_gt_i32_e32 vcc, 32, v244
	s_nop 1
	v_cndmask_b32_e32 v130, v130, v245, vcc
	v_cmp_gt_i32_e32 vcc, 33, v244
	s_nop 1
	v_cndmask_b32_e32 v131, v131, v245, vcc
	v_cmp_gt_i32_e32 vcc, 34, v244
	s_nop 1
	v_cndmask_b32_e32 v132, v132, v245, vcc
	v_cmp_gt_i32_e32 vcc, 35, v244
	s_nop 1
	v_cndmask_b32_e32 v133, v133, v245, vcc
	v_cmp_gt_i32_e32 vcc, 16, v244
	s_nop 1
	v_cndmask_b32_e32 v134, v134, v245, vcc
	v_cmp_gt_i32_e32 vcc, 17, v244
	s_nop 1
	v_cndmask_b32_e32 v135, v135, v245, vcc
	v_cmp_gt_i32_e32 vcc, 18, v244
	s_nop 1
	v_cndmask_b32_e32 v136, v136, v245, vcc
	v_cmp_gt_i32_e32 vcc, 19, v244
	s_nop 1
	v_cndmask_b32_e32 v137, v137, v245, vcc
	v_cmp_gt_i32_e32 vcc, 48, v244
	s_nop 1
	v_cndmask_b32_e32 v138, v138, v245, vcc
	v_cmp_gt_i32_e32 vcc, 49, v244
	s_nop 1
	v_cndmask_b32_e32 v139, v139, v245, vcc
	v_cmp_gt_i32_e32 vcc, 50, v244
	s_nop 1
	v_cndmask_b32_e32 v140, v140, v245, vcc
	v_cmp_gt_i32_e32 vcc, 51, v244
	s_nop 1
	v_cndmask_b32_e32 v141, v141, v245, vcc
	v_cmp_gt_i32_e32 vcc, 32, v244
	s_nop 1
	v_cndmask_b32_e32 v142, v142, v245, vcc
	v_cmp_gt_i32_e32 vcc, 33, v244
	s_nop 1
	v_cndmask_b32_e32 v143, v143, v245, vcc
	v_cmp_gt_i32_e32 vcc, 34, v244
	s_nop 1
	v_cndmask_b32_e32 v144, v144, v245, vcc
	v_cmp_gt_i32_e32 vcc, 35, v244
	s_nop 1
	v_cndmask_b32_e32 v145, v145, v245, vcc
.Lm16_nomask:
	v_exp_f32_e32 v114, v114
	v_exp_f32_e32 v115, v115
	v_exp_f32_e32 v116, v116
	v_exp_f32_e32 v117, v117
	v_exp_f32_e32 v118, v118
	v_exp_f32_e32 v119, v119
	v_exp_f32_e32 v120, v120
	v_exp_f32_e32 v121, v121
	v_exp_f32_e32 v122, v122
	v_exp_f32_e32 v123, v123
	v_exp_f32_e32 v124, v124
	v_exp_f32_e32 v125, v125
	v_exp_f32_e32 v126, v126
	v_exp_f32_e32 v127, v127
	v_exp_f32_e32 v128, v128
	v_exp_f32_e32 v129, v129
	v_exp_f32_e32 v130, v130
	v_exp_f32_e32 v131, v131
	v_exp_f32_e32 v132, v132
	v_exp_f32_e32 v133, v133
	v_exp_f32_e32 v134, v134
	v_exp_f32_e32 v135, v135
	v_exp_f32_e32 v136, v136
	v_exp_f32_e32 v137, v137
	v_exp_f32_e32 v138, v138
	v_exp_f32_e32 v139, v139
	v_exp_f32_e32 v140, v140
	v_exp_f32_e32 v141, v141
	v_exp_f32_e32 v142, v142
	v_exp_f32_e32 v143, v143
	v_exp_f32_e32 v144, v144
	v_exp_f32_e32 v145, v145
	v_cvt_pk_bf16_f32 v164, v114, v115
	v_cvt_pk_bf16_f32 v165, v116, v117
	v_cvt_pk_bf16_f32 v166, v122, v123
	v_cvt_pk_bf16_f32 v167, v124, v125
	v_cvt_pk_bf16_f32 v168, v130, v131
	v_cvt_pk_bf16_f32 v169, v132, v133
	v_cvt_pk_bf16_f32 v170, v138, v139
	v_cvt_pk_bf16_f32 v171, v140, v141
	v_cvt_pk_bf16_f32 v172, v118, v119
	v_cvt_pk_bf16_f32 v173, v120, v121
	v_cvt_pk_bf16_f32 v174, v126, v127
	v_cvt_pk_bf16_f32 v175, v128, v129
	v_cvt_pk_bf16_f32 v176, v134, v135
	v_cvt_pk_bf16_f32 v177, v136, v137
	v_cvt_pk_bf16_f32 v178, v142, v143
	v_cvt_pk_bf16_f32 v179, v144, v145
	v_or3_b32 v220, v164, v165, v166
	v_or3_b32 v221, v167, v168, v169
	v_or3_b32 v222, v170, v171, v172
	v_or3_b32 v223, v173, v174, v175
	v_or3_b32 v158, v176, v177, v178
	v_or3_b32 v220, v220, v221, v222
	v_or3_b32 v223, v223, v158, v179
	v_or_b32_e32 v220, v220, v223
	v_and_b32_e32 v220, 0x40004000, v220
	v_cmp_eq_u32_e32 vcc, 0, v220
	s_cmp_eq_u64 vcc, exec
	s_cbranch_scc1 .Lm16_pv
; #define WLK(n) do { asm volatile("s_waitcnt lgkmcnt(" #n ")" ::: "memory"); SBAR(); } while (0)
; #define RDN(S, dd, off) do { const int a_ = rb + (((dd) * 32 + h16) ^ sw); KRD(S##0, a_, off); KRD(S##1, a_, 8192 + (off)); } while (0)
; #define RDR(S, ks) do { const int a_ = rr + (((((ks) * 2 + hi)) ^ (r32 & 7)) << 4); KRD(S##0, a_, 0); KRD(S##1, a_, 4096); } while (0)
; #define MM1(S, d) do { p0 = __builtin_amdgcn_mfma_f32_32x32x16_bf16(S##0, qr[d], p0, 0, 0, 0); p1 = __builtin_amdgcn_mfma_f32_32x32x16_bf16(S##1, qr[d], p1, 0, 0, 0); } while (0)
; __device__ __forceinline__ void qk_mla(f32x16& p0, f32x16& p1, int kaddr, int r32, int hi, const bf16x8* qr) {
;     const int rb = kaddr + r32 * 256, sw = (r32 & 7) << 4, h16 = hi * 16;
;     const int rr = kaddr + 16384 + r32 * 128;
;     ...
;     bf16x8 A0, A1, B0, B1;
;     RDN(A, 0, 0); RDN(B, 1, 0);
;     WLK(2); MM1(A, 0); RDN(A, 2, 0);
;     WLK(2); MM1(B, 1); RDN(B, 3, 0);
;     WLK(2); MM1(A, 2); RDN(A, 0, 128);
;     WLK(2); MM1(B, 3); RDN(B, 1, 128);
;     WLK(2); MM1(A, 4); RDN(A, 2, 128);
;     WLK(2); MM1(B, 5); RDN(B, 3, 128);
;     WLK(2); MM1(A, 6); RDR(A, 0);
;     WLK(2); MM1(B, 7); RDR(B, 1);
;     WLK(2); MM1(A, 8); RDR(A, 2);
;     WLK(2); MM1(B, 9); RDR(B, 3);
;     WLK(2); MM1(A, 10);
;     WLK(0); MM1(B, 11);
	ds_read_b128 v[180:183], v228 offset:0
	ds_read_b128 v[184:187], v228 offset:2048
	ds_read_b128 v[188:191], v228 offset:4096
	ds_read_b128 v[192:195], v228 offset:6144
	s_waitcnt lgkmcnt(3)
	v_mfma_f32_16x16x32_bf16 v[114:117], v[180:183], v[66:69], v[208:211]
	v_mfma_f32_16x16x32_bf16 v[118:121], v[180:183], v[90:93], v[212:215]
	ds_read_b128 v[180:183], v229 offset:0
	s_waitcnt lgkmcnt(3)
	v_mfma_f32_16x16x32_bf16 v[122:125], v[184:187], v[66:69], v[208:211]
	v_mfma_f32_16x16x32_bf16 v[126:129], v[184:187], v[90:93], v[212:215]
	ds_read_b128 v[184:187], v229 offset:2048
	s_waitcnt lgkmcnt(3)
	v_mfma_f32_16x16x32_bf16 v[130:133], v[188:191], v[66:69], v[208:211]
	v_mfma_f32_16x16x32_bf16 v[134:137], v[188:191], v[90:93], v[212:215]
	ds_read_b128 v[188:191], v229 offset:4096
	s_waitcnt lgkmcnt(3)
	v_mfma_f32_16x16x32_bf16 v[138:141], v[192:195], v[66:69], v[208:211]
	v_mfma_f32_16x16x32_bf16 v[142:145], v[192:195], v[90:93], v[212:215]
	ds_read_b128 v[192:195], v229 offset:6144
	s_waitcnt lgkmcnt(3)
	v_mfma_f32_16x16x32_bf16 v[114:117], v[180:183], v[70:73], v[114:117]
	v_mfma_f32_16x16x32_bf16 v[118:121], v[180:183], v[94:97], v[118:121]
	ds_read_b128 v[180:183], v228 offset:8192
	s_waitcnt lgkmcnt(3)
	v_mfma_f32_16x16x32_bf16 v[122:125], v[184:187], v[70:73], v[122:125]
	v_mfma_f32_16x16x32_bf16 v[126:129], v[184:187], v[94:97], v[126:129]
	ds_read_b128 v[184:187], v228 offset:10240
	s_waitcnt lgkmcnt(3)
	v_mfma_f32_16x16x32_bf16 v[130:133], v[188:191], v[70:73], v[130:133]
	v_mfma_f32_16x16x32_bf16 v[134:137], v[188:191], v[94:97], v[134:137]
	ds_read_b128 v[188:191], v228 offset:12288
	s_waitcnt lgkmcnt(3)
	v_mfma_f32_16x16x32_bf16 v[138:141], v[192:195], v[70:73], v[138:141]
	v_mfma_f32_16x16x32_bf16 v[142:145], v[192:195], v[94:97], v[142:145]
	ds_read_b128 v[192:195], v228 offset:14336
	s_waitcnt lgkmcnt(3)
	v_mfma_f32_16x16x32_bf16 v[114:117], v[180:183], v[74:77], v[114:117]
	v_mfma_f32_16x16x32_bf16 v[118:121], v[180:183], v[98:101], v[118:121]
	ds_read_b128 v[180:183], v229 offset:8192
	s_waitcnt lgkmcnt(3)
	v_mfma_f32_16x16x32_bf16 v[122:125], v[184:187], v[74:77], v[122:125]
	v_mfma_f32_16x16x32_bf16 v[126:129], v[184:187], v[98:101], v[126:129]
	ds_read_b128 v[184:187], v229 offset:10240
	s_waitcnt lgkmcnt(3)
	v_mfma_f32_16x16x32_bf16 v[130:133], v[188:191], v[74:77], v[130:133]
	v_mfma_f32_16x16x32_bf16 v[134:137], v[188:191], v[98:101], v[134:137]
	ds_read_b128 v[188:191], v229 offset:12288
	s_waitcnt lgkmcnt(3)
	v_mfma_f32_16x16x32_bf16 v[138:141], v[192:195], v[74:77], v[138:141]
	v_mfma_f32_16x16x32_bf16 v[142:145], v[192:195], v[98:101], v[142:145]
	ds_read_b128 v[192:195], v229 offset:14336
	s_waitcnt lgkmcnt(3)
	v_mfma_f32_16x16x32_bf16 v[114:117], v[180:183], v[78:81], v[114:117]
	v_mfma_f32_16x16x32_bf16 v[118:121], v[180:183], v[102:105], v[118:121]
	ds_read_b128 v[180:183], v228 offset:16384
	s_waitcnt lgkmcnt(3)
	v_mfma_f32_16x16x32_bf16 v[122:125], v[184:187], v[78:81], v[122:125]
	v_mfma_f32_16x16x32_bf16 v[126:129], v[184:187], v[102:105], v[126:129]
	ds_read_b128 v[184:187], v228 offset:18432
	s_waitcnt lgkmcnt(3)
	v_mfma_f32_16x16x32_bf16 v[130:133], v[188:191], v[78:81], v[130:133]
	v_mfma_f32_16x16x32_bf16 v[134:137], v[188:191], v[102:105], v[134:137]
	ds_read_b128 v[188:191], v228 offset:20480
	s_waitcnt lgkmcnt(3)
	v_mfma_f32_16x16x32_bf16 v[138:141], v[192:195], v[78:81], v[138:141]
	v_mfma_f32_16x16x32_bf16 v[142:145], v[192:195], v[102:105], v[142:145]
	ds_read_b128 v[192:195], v228 offset:22528
	s_waitcnt lgkmcnt(3)
	v_mfma_f32_16x16x32_bf16 v[114:117], v[180:183], v[82:85], v[114:117]
	v_mfma_f32_16x16x32_bf16 v[118:121], v[180:183], v[106:109], v[118:121]
	ds_read_b128 v[180:183], v229 offset:16384
	s_waitcnt lgkmcnt(3)
	v_mfma_f32_16x16x32_bf16 v[122:125], v[184:187], v[82:85], v[122:125]
	v_mfma_f32_16x16x32_bf16 v[126:129], v[184:187], v[106:109], v[126:129]
	ds_read_b128 v[184:187], v229 offset:18432
	s_waitcnt lgkmcnt(3)
	v_mfma_f32_16x16x32_bf16 v[130:133], v[188:191], v[82:85], v[130:133]
	v_mfma_f32_16x16x32_bf16 v[134:137], v[188:191], v[106:109], v[134:137]
	ds_read_b128 v[188:191], v229 offset:20480
	s_waitcnt lgkmcnt(3)
	v_mfma_f32_16x16x32_bf16 v[138:141], v[192:195], v[82:85], v[138:141]
	v_mfma_f32_16x16x32_bf16 v[142:145], v[192:195], v[106:109], v[142:145]
	ds_read_b128 v[192:195], v229 offset:22528
	s_waitcnt lgkmcnt(3)
	v_mfma_f32_16x16x32_bf16 v[114:117], v[180:183], v[86:89], v[114:117]
	v_mfma_f32_16x16x32_bf16 v[118:121], v[180:183], v[110:113], v[118:121]
	s_waitcnt lgkmcnt(2)
	v_mfma_f32_16x16x32_bf16 v[122:125], v[184:187], v[86:89], v[122:125]
	v_mfma_f32_16x16x32_bf16 v[126:129], v[184:187], v[110:113], v[126:129]
	s_waitcnt lgkmcnt(1)
	v_mfma_f32_16x16x32_bf16 v[130:133], v[188:191], v[86:89], v[130:133]
	v_mfma_f32_16x16x32_bf16 v[134:137], v[188:191], v[110:113], v[134:137]
	s_waitcnt lgkmcnt(0)
	v_mfma_f32_16x16x32_bf16 v[138:141], v[192:195], v[86:89], v[138:141]
	v_mfma_f32_16x16x32_bf16 v[142:145], v[192:195], v[110:113], v[142:145]
	ds_read_b64_tr_b16 v[180:181], v230 offset:0
	ds_read_b64_tr_b16 v[182:183], v230 offset:4096
	ds_read_b64_tr_b16 v[184:185], v230 offset:8192
	ds_read_b64_tr_b16 v[186:187], v230 offset:12288
	ds_read_b64_tr_b16 v[188:189], v231 offset:0
	ds_read_b64_tr_b16 v[190:191], v231 offset:4096
	s_nop 7
	s_add_u32 s36, s42, 63
	s_cmp_gt_u32 s36, s43
	s_cbranch_scc0 .Lm16_nomask_s
; __device__ __forceinline__ void mask_tile(f32x16& p0, f32x16& p1, int dq, unsigned W) {
;     const float NEG = -__builtin_inff();
; #pragma unroll
;     for (int r = 0; r < 16; ++r) { const int c = (r & 3) + 8 * (r >> 2);
;         if ((unsigned)(dq - c) >= W) p0[r] = NEG;
;         if ((unsigned)(dq - c - 32) >= W) p1[r] = NEG; }
; }
	s_sub_u32 s36, s43, s42
	v_add_u32_e32 v244, s36, v243
	v_cmp_gt_i32_e32 vcc, 0, v244
	s_nop 1
	v_cndmask_b32_e32 v114, v114, v245, vcc
	v_cmp_gt_i32_e32 vcc, 1, v244
	s_nop 1
	v_cndmask_b32_e32 v115, v115, v245, vcc
	v_cmp_gt_i32_e32 vcc, 2, v244
	s_nop 1
	v_cndmask_b32_e32 v116, v116, v245, vcc
	v_cmp_gt_i32_e32 vcc, 3, v244
	s_nop 1
	v_cndmask_b32_e32 v117, v117, v245, vcc
	v_cmp_gt_i32_e32 vcc, -16, v244
	s_nop 1
	v_cndmask_b32_e32 v118, v118, v245, vcc
	v_cmp_gt_i32_e32 vcc, -15, v244
	s_nop 1
	v_cndmask_b32_e32 v119, v119, v245, vcc
	v_cmp_gt_i32_e32 vcc, -14, v244
	s_nop 1
	v_cndmask_b32_e32 v120, v120, v245, vcc
	v_cmp_gt_i32_e32 vcc, -13, v244
	s_nop 1
	v_cndmask_b32_e32 v121, v121, v245, vcc
	v_cmp_gt_i32_e32 vcc, 16, v244
	s_nop 1
	v_cndmask_b32_e32 v122, v122, v245, vcc
	v_cmp_gt_i32_e32 vcc, 17, v244
	s_nop 1
	v_cndmask_b32_e32 v123, v123, v245, vcc
	v_cmp_gt_i32_e32 vcc, 18, v244
	s_nop 1
	v_cndmask_b32_e32 v124, v124, v245, vcc
	v_cmp_gt_i32_e32 vcc, 19, v244
	s_nop 1
	v_cndmask_b32_e32 v125, v125, v245, vcc
	v_cmp_gt_i32_e32 vcc, 0, v244
	s_nop 1
	v_cndmask_b32_e32 v126, v126, v245, vcc
	v_cmp_gt_i32_e32 vcc, 1, v244
	s_nop 1
	v_cndmask_b32_e32 v127, v127, v245, vcc
	v_cmp_gt_i32_e32 vcc, 2, v244
	s_nop 1
	v_cndmask_b32_e32 v128, v128, v245, vcc
	v_cmp_gt_i32_e32 vcc, 3, v244
	s_nop 1
	v_cndmask_b32_e32 v129, v129, v245, vcc
	v_cmp_gt_i32_e32 vcc, 32, v244
	s_nop 1
	v_cndmask_b32_e32 v130, v130, v245, vcc
	v_cmp_gt_i32_e32 vcc, 33, v244
	s_nop 1
	v_cndmask_b32_e32 v131, v131, v245, vcc
	v_cmp_gt_i32_e32 vcc, 34, v244
	s_nop 1
	v_cndmask_b32_e32 v132, v132, v245, vcc
	v_cmp_gt_i32_e32 vcc, 35, v244
	s_nop 1
	v_cndmask_b32_e32 v133, v133, v245, vcc
	v_cmp_gt_i32_e32 vcc, 16, v244
	s_nop 1
	v_cndmask_b32_e32 v134, v134, v245, vcc
	v_cmp_gt_i32_e32 vcc, 17, v244
	s_nop 1
	v_cndmask_b32_e32 v135, v135, v245, vcc
	v_cmp_gt_i32_e32 vcc, 18, v244
	s_nop 1
	v_cndmask_b32_e32 v136, v136, v245, vcc
	v_cmp_gt_i32_e32 vcc, 19, v244
	s_nop 1
	v_cndmask_b32_e32 v137, v137, v245, vcc
	v_cmp_gt_i32_e32 vcc, 48, v244
	s_nop 1
	v_cndmask_b32_e32 v138, v138, v245, vcc
	v_cmp_gt_i32_e32 vcc, 49, v244
	s_nop 1
	v_cndmask_b32_e32 v139, v139, v245, vcc
	v_cmp_gt_i32_e32 vcc, 50, v244
	s_nop 1
	v_cndmask_b32_e32 v140, v140, v245, vcc
	v_cmp_gt_i32_e32 vcc, 51, v244
	s_nop 1
	v_cndmask_b32_e32 v141, v141, v245, vcc
	v_cmp_gt_i32_e32 vcc, 32, v244
	s_nop 1
	v_cndmask_b32_e32 v142, v142, v245, vcc
	v_cmp_gt_i32_e32 vcc, 33, v244
	s_nop 1
	v_cndmask_b32_e32 v143, v143, v245, vcc
	v_cmp_gt_i32_e32 vcc, 34, v244
	s_nop 1
	v_cndmask_b32_e32 v144, v144, v245, vcc
	v_cmp_gt_i32_e32 vcc, 35, v244
	s_nop 1
	v_cndmask_b32_e32 v145, v145, v245, vcc

; #define PV_RD(S, d0) do { constexpr int b_ = (d0) * 512; TRRD(S##l0, b_); TRRD(S##h0, b_ + KS_ / 2); TRRD(S##l1, b_ + KS_); TRRD(S##h1, b_ + KS_ + KS_ / 2); TRRD(S##l2, b_ + 2 * KS_); TRRD(S##h2, b_ + 2 * KS_ + KS_ / 2); TRRD(S##l3, b_ + 3 * KS_); TRRD(S##h3, b_ + 3 * KS_ + KS_ / 2); } while (0)
; #define WL(n) do { asm volatile("s_waitcnt lgkmcnt(" #n ")" ::: "memory"); SBAR(); } while (0)
; template <int NCB> __device__ __forceinline__ void pv_tile(f32x16* o, int vb, bf16x8 pa0, bf16x8 pa1, bf16x8 pa2, bf16x8 pa3) {
;     ...
;     constexpr int KS_ = NCB * 1024;
;     ...
;     s16x4 Al0, Al1, Al2, Al3, Ah0, Ah1, Ah2, Ah3, Bl0, Bl1, Bl2, Bl3, Bh0, Bh1, Bh2, Bh3;
;     PV_RD(A, 0); PV_RD(B, 1); WL(8); PV_MM(A, 0);
;     if constexpr (NCB == 4) { PV_RD(A, 2); WL(8); PV_MM(B, 1); PV_RD(B, 3); WL(8); PV_MM(A, 2); WL(0); PV_MM(B, 3); }
;     else { WL(0); PV_MM(B, 1); }
; template <bool MLA> __device__ __forceinline__ void attn_unit(const AttnP& P, int b, int hh, int qb, LAS char* lds) {
;     ...
;     for (int t = 0; t < NT; ++t) {
;         const int buf = t & 1;
;         if (t + 1 < NT) LOADT(t + 1, buf ^ 1);
;         const int kb = kbase0 + 64 * t;
;         const bool act = (kb <= qlo + 31) && (MLA || kb + 63 >= qlo - (W - 1));
.Lm16_pv:
	ds_read_b64_tr_b16 v[192:193], v231 offset:8192
	ds_read_b64_tr_b16 v[194:195], v231 offset:12288
	s_waitcnt lgkmcnt(6)
	v_mfma_f32_16x16x32_bf16 v[2:5], v[180:183], v[164:167], v[2:5]
	v_mfma_f32_16x16x32_bf16 v[6:9], v[180:183], v[172:175], v[6:9]
	v_mfma_f32_16x16x32_bf16 v[146:149], v[154:157], v[164:167], v[146:149]
	v_mfma_f32_16x16x32_bf16 v[150:153], v[154:157], v[172:175], v[150:153]
	ds_read_b64_tr_b16 v[180:181], v230 offset:512
	ds_read_b64_tr_b16 v[182:183], v230 offset:4608
	s_waitcnt lgkmcnt(6)
	v_mfma_f32_16x16x32_bf16 v[2:5], v[184:187], v[168:171], v[2:5]
	v_mfma_f32_16x16x32_bf16 v[6:9], v[184:187], v[176:179], v[6:9]
	v_mfma_f32_16x16x32_bf16 v[146:149], v[154:157], v[168:171], v[146:149]
	v_mfma_f32_16x16x32_bf16 v[150:153], v[154:157], v[176:179], v[150:153]
	ds_read_b64_tr_b16 v[184:185], v230 offset:8704
	ds_read_b64_tr_b16 v[186:187], v230 offset:12800
	s_waitcnt lgkmcnt(6)
	v_mfma_f32_16x16x32_bf16 v[10:13], v[188:191], v[164:167], v[10:13]
	v_mfma_f32_16x16x32_bf16 v[14:17], v[188:191], v[172:175], v[14:17]
	ds_read_b64_tr_b16 v[188:189], v231 offset:512
	ds_read_b64_tr_b16 v[190:191], v231 offset:4608
	s_waitcnt lgkmcnt(6)
	v_mfma_f32_16x16x32_bf16 v[10:13], v[192:195], v[168:171], v[10:13]
	v_mfma_f32_16x16x32_bf16 v[14:17], v[192:195], v[176:179], v[14:17]
	ds_read_b64_tr_b16 v[192:193], v231 offset:8704
	ds_read_b64_tr_b16 v[194:195], v231 offset:12800
	s_waitcnt lgkmcnt(6)
	v_mfma_f32_16x16x32_bf16 v[18:21], v[180:183], v[164:167], v[18:21]
	v_mfma_f32_16x16x32_bf16 v[22:25], v[180:183], v[172:175], v[22:25]
	ds_read_b64_tr_b16 v[180:181], v230 offset:1024
	ds_read_b64_tr_b16 v[182:183], v230 offset:5120
	s_waitcnt lgkmcnt(6)
	v_mfma_f32_16x16x32_bf16 v[18:21], v[184:187], v[168:171], v[18:21]
	v_mfma_f32_16x16x32_bf16 v[22:25], v[184:187], v[176:179], v[22:25]
	ds_read_b64_tr_b16 v[184:185], v230 offset:9216
	ds_read_b64_tr_b16 v[186:187], v230 offset:13312
	s_waitcnt lgkmcnt(6)
	v_mfma_f32_16x16x32_bf16 v[26:29], v[188:191], v[164:167], v[26:29]
	v_mfma_f32_16x16x32_bf16 v[30:33], v[188:191], v[172:175], v[30:33]
	ds_read_b64_tr_b16 v[188:189], v231 offset:1024
	ds_read_b64_tr_b16 v[190:191], v231 offset:5120
	s_waitcnt lgkmcnt(6)
	v_mfma_f32_16x16x32_bf16 v[26:29], v[192:195], v[168:171], v[26:29]
	v_mfma_f32_16x16x32_bf16 v[30:33], v[192:195], v[176:179], v[30:33]
	ds_read_b64_tr_b16 v[192:193], v231 offset:9216
	ds_read_b64_tr_b16 v[194:195], v231 offset:13312
	s_waitcnt lgkmcnt(6)
	v_mfma_f32_16x16x32_bf16 v[34:37], v[180:183], v[164:167], v[34:37]
	v_mfma_f32_16x16x32_bf16 v[38:41], v[180:183], v[172:175], v[38:41]
	ds_read_b64_tr_b16 v[180:181], v230 offset:1536
	ds_read_b64_tr_b16 v[182:183], v230 offset:5632
	s_waitcnt lgkmcnt(6)
	v_mfma_f32_16x16x32_bf16 v[34:37], v[184:187], v[168:171], v[34:37]
	v_mfma_f32_16x16x32_bf16 v[38:41], v[184:187], v[176:179], v[38:41]
	ds_read_b64_tr_b16 v[184:185], v230 offset:9728
	ds_read_b64_tr_b16 v[186:187], v230 offset:13824
	s_waitcnt lgkmcnt(6)
	v_mfma_f32_16x16x32_bf16 v[42:45], v[188:191], v[164:167], v[42:45]
	v_mfma_f32_16x16x32_bf16 v[46:49], v[188:191], v[172:175], v[46:49]
	ds_read_b64_tr_b16 v[188:189], v231 offset:1536
	ds_read_b64_tr_b16 v[190:191], v231 offset:5632
	s_waitcnt lgkmcnt(6)
	v_mfma_f32_16x16x32_bf16 v[42:45], v[192:195], v[168:171], v[42:45]
	v_mfma_f32_16x16x32_bf16 v[46:49], v[192:195], v[176:179], v[46:49]
	ds_read_b64_tr_b16 v[192:193], v231 offset:9728
	ds_read_b64_tr_b16 v[194:195], v231 offset:13824
	s_waitcnt lgkmcnt(6)
	v_mfma_f32_16x16x32_bf16 v[50:53], v[180:183], v[164:167], v[50:53]
	v_mfma_f32_16x16x32_bf16 v[54:57], v[180:183], v[172:175], v[54:57]
	s_waitcnt lgkmcnt(4)
	v_mfma_f32_16x16x32_bf16 v[50:53], v[184:187], v[168:171], v[50:53]
	v_mfma_f32_16x16x32_bf16 v[54:57], v[184:187], v[176:179], v[54:57]
	s_waitcnt lgkmcnt(2)
	v_mfma_f32_16x16x32_bf16 v[58:61], v[188:191], v[164:167], v[58:61]
	v_mfma_f32_16x16x32_bf16 v[62:65], v[188:191], v[172:175], v[62:65]
	s_waitcnt lgkmcnt(0)
	v_mfma_f32_16x16x32_bf16 v[58:61], v[192:195], v[168:171], v[58:61]
	v_mfma_f32_16x16x32_bf16 v[62:65], v[192:195], v[176:179], v[62:65]
	s_branch .Lm16_tile_end
.Lm16_inactive:
	s_add_u32 s36, s41, 1
	s_cmp_lt_u32 s36, s40
	s_cbranch_scc0 .Lm16_noload_i
	s_xor_b32 s37, s58, 1
	s_mul_i32 s59, s37, 0x6000
	s_add_u32 s59, s59, 0x8000
	s_lshl_b32 s37, s37, 14
	s_add_i32 s36, s5, s59
	s_mov_b32 m0, s36
	s_nop 0
	global_load_lds_dwordx4 v232, s[46:47]
	s_add_i32 m0, s36, 0x2000
	s_nop 0
	global_load_lds_dwordx4 v233, s[46:47]
	s_add_i32 m0, s36, 0x4000
	s_nop 0
	global_load_lds_dwordx4 v234, s[50:51]
	s_add_i32 s36, s5, s37
	s_mov_b32 m0, s36
	s_nop 0
	global_load_lds_dwordx4 v235, s[48:49]
	s_add_i32 m0, s36, 0x2000
	s_nop 0
	global_load_lds_dwordx4 v236, s[48:49]
	s_add_u32 s46, s46, 0x40000
	s_addc_u32 s47, s47, 0
	s_add_u32 s48, s48, 0x40000
	s_addc_u32 s49, s49, 0
	s_add_u32 s50, s50, 0x2000
	s_addc_u32 s51, s51, 0
; #define LAS __attribute__((address_space(3)))
; __device__ __forceinline__ int crow(int r, int hi) { return (r & 3) + 8 * (r >> 2) + 4 * hi; }
; __device__ __forceinline__ unsigned cvtpk(float lo, float hi) { f32x2_cv v = {lo, hi}; bf16x2_cv b = __builtin_convertvector(v, bf16x2_cv); return __builtin_bit_cast(unsigned, b); }
; #define WRITET(bf) do { if constexpr (!MLA) { *(LAS bf16x8*)(K_lds + (bf) * KBYTES + kws) = sk0; *(LAS bf16x8*)(V_lds + (bf) * VBYTES + vst0) = sv0; } } while (0)
; template <bool MLA> __device__ __forceinline__ void attn_unit(const AttnP& P, int b, int hh, int qb, LAS char* lds) {
;     ...
;         if (t + 1 < NT) { asm volatile("s_waitcnt vmcnt(0)" ::: "memory"); WRITET(buf ^ 1); }
;         __syncthreads();
;     }
;     if (hi == 0) li_l[r32] = l_reg; asm volatile("s_waitcnt lgkmcnt(0)" ::: "memory");
;     bf16_t* Ow = (MLA ? P.QN + (rowbase + qlo) * 2048 + hh * 128 : P.QS + (rowbase + qlo) * 2048 + hh * 64);
; #pragma unroll
;     for (int r = 0; r < 16; ++r) { const int orow = crow(r, hi); const float rl = __builtin_amdgcn_rcpf(li_l[orow]);
; #pragma unroll
;         for (int d0 = 0; d0 < NCB; ++d0) { const float v = o[d0][r] * rl; const float vn = __shfl_xor(v, 1);
;             if ((r32 & 1) == 0) *(unsigned*)(Ow + (size_t)orow * 2048 + d0 * 32 + r32) = cvtpk(v, vn); } }
; __global__ void __launch_bounds__(512) fwd_mega(Args a) {
;     ...
;         for (int it = vcu; it < 1024; it += G) { const int bh = it >> 5, s = it & 31;
;             att::attn_unit<true>(P, bh >> 4, bh & 15, 63 - s, (LAS char*)lds);
;             att::attn_unit<true>(P, bh >> 4, bh & 15, s, (LAS char*)lds); }
.Lm16_noload_i:
.Lm16_tile_end:
	s_waitcnt vmcnt(0) lgkmcnt(0)
	s_barrier
	s_add_u32 s41, s41, 1
	s_add_u32 s42, s42, 64
	s_cmp_lt_u32 s41, s40
	s_cbranch_scc1 .Lm16_tile
	s_nop 7
	v_rcp_f32_e32 v216, v146
	v_rcp_f32_e32 v217, v150
	s_nop 0
	v_mul_f32_e32 v2, v2, v216
	v_mul_f32_e32 v3, v3, v216
	v_mul_f32_e32 v4, v4, v216
	v_mul_f32_e32 v5, v5, v216
	v_cvt_pk_bf16_f32 v2, v2, v3
	v_cvt_pk_bf16_f32 v3, v4, v5
	global_store_dwordx2 v241, v[2:3], s[66:67] offset:0
	v_mul_f32_e32 v6, v6, v217
	v_mul_f32_e32 v7, v7, v217
	v_mul_f32_e32 v8, v8, v217
	v_mul_f32_e32 v9, v9, v217
	v_cvt_pk_bf16_f32 v6, v6, v7
	v_cvt_pk_bf16_f32 v7, v8, v9
	global_store_dwordx2 v242, v[6:7], s[66:67] offset:0
	v_mul_f32_e32 v10, v10, v216
	v_mul_f32_e32 v11, v11, v216
	v_mul_f32_e32 v12, v12, v216
	v_mul_f32_e32 v13, v13, v216
	v_cvt_pk_bf16_f32 v10, v10, v11
	v_cvt_pk_bf16_f32 v11, v12, v13
	global_store_dwordx2 v241, v[10:11], s[66:67] offset:32
	v_mul_f32_e32 v14, v14, v217
	v_mul_f32_e32 v15, v15, v217
	v_mul_f32_e32 v16, v16, v217
	v_mul_f32_e32 v17, v17, v217
	v_cvt_pk_bf16_f32 v14, v14, v15
	v_cvt_pk_bf16_f32 v15, v16, v17
	global_store_dwordx2 v242, v[14:15], s[66:67] offset:32
	v_mul_f32_e32 v18, v18, v216
	v_mul_f32_e32 v19, v19, v216
	v_mul_f32_e32 v20, v20, v216
	v_mul_f32_e32 v21, v21, v216
	v_cvt_pk_bf16_f32 v18, v18, v19
	v_cvt_pk_bf16_f32 v19, v20, v21
	global_store_dwordx2 v241, v[18:19], s[66:67] offset:64
	v_mul_f32_e32 v22, v22, v217
	v_mul_f32_e32 v23, v23, v217
	v_mul_f32_e32 v24, v24, v217
	v_mul_f32_e32 v25, v25, v217
	v_cvt_pk_bf16_f32 v22, v22, v23
	v_cvt_pk_bf16_f32 v23, v24, v25
	global_store_dwordx2 v242, v[22:23], s[66:67] offset:64
	v_mul_f32_e32 v26, v26, v216
	v_mul_f32_e32 v27, v27, v216
	v_mul_f32_e32 v28, v28, v216
	v_mul_f32_e32 v29, v29, v216
	v_cvt_pk_bf16_f32 v26, v26, v27
	v_cvt_pk_bf16_f32 v27, v28, v29
	global_store_dwordx2 v241, v[26:27], s[66:67] offset:96
	v_mul_f32_e32 v30, v30, v217
	v_mul_f32_e32 v31, v31, v217
	v_mul_f32_e32 v32, v32, v217
	v_mul_f32_e32 v33, v33, v217
	v_cvt_pk_bf16_f32 v30, v30, v31
	v_cvt_pk_bf16_f32 v31, v32, v33
	global_store_dwordx2 v242, v[30:31], s[66:67] offset:96
	v_mul_f32_e32 v34, v34, v216
	v_mul_f32_e32 v35, v35, v216
	v_mul_f32_e32 v36, v36, v216
	v_mul_f32_e32 v37, v37, v216
	v_cvt_pk_bf16_f32 v34, v34, v35
	v_cvt_pk_bf16_f32 v35, v36, v37
	global_store_dwordx2 v241, v[34:35], s[66:67] offset:128
	v_mul_f32_e32 v38, v38, v217
	v_mul_f32_e32 v39, v39, v217
	v_mul_f32_e32 v40, v40, v217
	v_mul_f32_e32 v41, v41, v217
	v_cvt_pk_bf16_f32 v38, v38, v39
	v_cvt_pk_bf16_f32 v39, v40, v41
	global_store_dwordx2 v242, v[38:39], s[66:67] offset:128
	v_mul_f32_e32 v42, v42, v216
	v_mul_f32_e32 v43, v43, v216
	v_mul_f32_e32 v44, v44, v216
	v_mul_f32_e32 v45, v45, v216
	v_cvt_pk_bf16_f32 v42, v42, v43
	v_cvt_pk_bf16_f32 v43, v44, v45
	global_store_dwordx2 v241, v[42:43], s[66:67] offset:160
	v_mul_f32_e32 v46, v46, v217
	v_mul_f32_e32 v47, v47, v217
	v_mul_f32_e32 v48, v48, v217
	v_mul_f32_e32 v49, v49, v217
	v_cvt_pk_bf16_f32 v46, v46, v47
	v_cvt_pk_bf16_f32 v47, v48, v49
	global_store_dwordx2 v242, v[46:47], s[66:67] offset:160
	v_mul_f32_e32 v50, v50, v216
	v_mul_f32_e32 v51, v51, v216
	v_mul_f32_e32 v52, v52, v216
	v_mul_f32_e32 v53, v53, v216
	v_cvt_pk_bf16_f32 v50, v50, v51
	v_cvt_pk_bf16_f32 v51, v52, v53
	global_store_dwordx2 v241, v[50:51], s[66:67] offset:192
	v_mul_f32_e32 v54, v54, v217
	v_mul_f32_e32 v55, v55, v217
	v_mul_f32_e32 v56, v56, v217
	v_mul_f32_e32 v57, v57, v217
	v_cvt_pk_bf16_f32 v54, v54, v55
	v_cvt_pk_bf16_f32 v55, v56, v57
	global_store_dwordx2 v242, v[54:55], s[66:67] offset:192
	v_mul_f32_e32 v58, v58, v216
	v_mul_f32_e32 v59, v59, v216
	v_mul_f32_e32 v60, v60, v216
	v_mul_f32_e32 v61, v61, v216
	v_cvt_pk_bf16_f32 v58, v58, v59
	v_cvt_pk_bf16_f32 v59, v60, v61
	global_store_dwordx2 v241, v[58:59], s[66:67] offset:224
	v_mul_f32_e32 v62, v62, v217
	v_mul_f32_e32 v63, v63, v217
	v_mul_f32_e32 v64, v64, v217
	v_mul_f32_e32 v65, v65, v217
	v_cvt_pk_bf16_f32 v62, v62, v63
	v_cvt_pk_bf16_f32 v63, v64, v65
	global_store_dwordx2 v242, v[62:63], s[66:67] offset:224
	s_add_u32 s29, s29, 1
	s_cmp_lt_u32 s29, 2
	s_cbranch_scc1 .Lm16_unit
	s_add_u32 s28, s28, s3
	s_cmp_lt_u32 s28, 0x400
	s_cbranch_scc1 .Lm16_item
	s_waitcnt vmcnt(0) lgkmcnt(0)
